# rwkv tiles: interior chunks stage the next chunk with direct global->LDS loads after the light-prep barrier (no register prefetch / LDS stash); edge chunks unchanged
# speedup vs baseline: 1.0019x; 1.0019x over previous
.LBB0_1411:
	s_add_i32 s52, s28, 1
	s_cmpk_eq_i32 s28, 0x87
	s_cbranch_scc1 .Lrw_du_nopf
	s_lshl_b32 s53, s52, 5
	s_sub_i32 s54, 0x11e0, s53
	s_and_b64 s[50:51], s[36:37], exec
	s_cselect_b32 s53, s53, s54
	s_add_i32 s54, s53, -1
	s_cmpk_eq_u32 s52, 0x87
	s_cbranch_scc1 .Lrw_du_pfslow
	s_branch .Lrw_du_nopf

.LBB0_1429:
	s_add_i32 s52, s28, 1
	s_cmpk_eq_u32 s28, 0x87
	s_cbranch_scc1 .Lrw_du_nodma
	s_cmpk_eq_u32 s52, 0x87
	s_cbranch_scc1 .Lrw_du_nodma
	s_lshl_b32 s53, s52, 5
	s_sub_i32 s54, 0x11e0, s53
	s_and_b64 s[50:51], s[36:37], exec
	s_cselect_b32 s53, s53, s54
	s_add_i32 s54, s53, -1
	v_readfirstlane_b32 s0, v104
	s_mov_b64 s[50:51], exec
	s_and_b64 exec, exec, s[42:43]
	v_add_u32_e32 v28, s54, v97
	v_lshlrev_b32_e32 v28, 11, v28
	v_mov_b32_e32 v29, v164
	s_mov_b32 m0, s0
	v_lshl_add_u64 v[28:29], v[80:81], 0, v[28:29]
	global_load_lds_dwordx4 v[28:29], off
	v_add_u32_e32 v28, s54, v98
	v_lshlrev_b32_e32 v28, 11, v28
	v_mov_b32_e32 v29, v164
	s_add_i32 m0, s0, 0xf00
	v_lshl_add_u64 v[28:29], v[80:81], 0, v[28:29]
	global_load_lds_dwordx4 v[28:29], off
	v_add_u32_e32 v28, s54, v99
	v_lshlrev_b32_e32 v28, 11, v28
	v_mov_b32_e32 v29, v164
	s_add_i32 m0, s0, 0x1e00
	v_lshl_add_u64 v[28:29], v[80:81], 0, v[28:29]
	global_load_lds_dwordx4 v[28:29], off
	v_add_u32_e32 v28, s53, v97
	v_mov_b32_e32 v29, v164
	v_lshlrev_b64 v[28:29], 10, v[28:29]
	s_add_i32 m0, s0, 0x3300
	v_lshl_add_u64 v[28:29], v[82:83], 0, v[28:29]
	global_load_lds_dwordx4 v[28:29], off
	v_add_u32_e32 v28, s53, v98
	v_mov_b32_e32 v29, v164
	v_lshlrev_b64 v[28:29], 10, v[28:29]
	s_add_i32 m0, s0, 0x4200
	v_lshl_add_u64 v[28:29], v[82:83], 0, v[28:29]
	global_load_lds_dwordx4 v[28:29], off
	v_add_u32_e32 v28, s53, v99
	v_mov_b32_e32 v29, v164
	v_lshlrev_b64 v[28:29], 10, v[28:29]
	s_add_i32 m0, s0, 0x5100
	v_lshl_add_u64 v[28:29], v[82:83], 0, v[28:29]
	global_load_lds_dwordx4 v[28:29], off
	s_and_b64 exec, exec, s[44:45]
	v_add_u32_e32 v28, s54, v100
	v_lshlrev_b32_e32 v28, 11, v28
	v_mov_b32_e32 v29, v164
	s_add_i32 m0, s0, 0x2d00
	v_lshl_add_u64 v[28:29], v[80:81], 0, v[28:29]
	global_load_lds_dwordx4 v[28:29], off
	s_mov_b64 exec, s[50:51]
	s_and_b64 exec, exec, s[42:43]
	s_and_b64 exec, exec, s[46:47]
	v_add_u32_e32 v28, s53, v100
	v_mov_b32_e32 v29, v164
	v_lshlrev_b64 v[28:29], 10, v[28:29]
	s_add_i32 m0, s0, 0x6000
	v_lshl_add_u64 v[28:29], v[82:83], 0, v[28:29]
	global_load_lds_dwordx4 v[28:29], off
	s_mov_b64 exec, s[50:51]

.LBB0_1436:
	s_and_b64 s[50:51], s[42:43], s[48:49]
	s_and_saveexec_b64 s[48:49], s[50:51]
	s_cbranch_execz .LBB0_1410
	s_waitcnt vmcnt(4)
	s_cmpk_lg_u32 s52, 0x87
	s_cbranch_scc1 .LBB0_1410
	ds_write_b128 v104, v[32:35]
	ds_write_b128 v105, v[28:31]
	ds_write_b128 v106, v[36:39]
	s_and_saveexec_b64 s[50:51], s[44:45]
	ds_write_b128 v120, v[40:43]
	s_or_b64 exec, exec, s[50:51]
	ds_write_b128 v104, v[44:47] offset:13056
	ds_write_b128 v105, v[48:51] offset:13056
	ds_write_b128 v106, v[52:55] offset:13056
	s_and_b64 exec, exec, s[46:47]
	s_cbranch_execz .LBB0_1410
	ds_write_b128 v120, v[56:59] offset:13056
	s_branch .LBB0_1410

.LBB0_1468:
	s_add_i32 s56, s28, 1
	v_readlane_b32 s0, v254, 14
	s_cmp_ge_u32 s56, s0
	s_cbranch_scc1 .Lrw_nd_nopf
	s_lshl_b32 s57, s56, 5
	s_sub_i32 s58, 0xe0, s57
	s_and_b64 s[50:51], s[36:37], exec
	s_cselect_b32 s64, s57, s58
	s_sub_i32 s58, 0x11e0, s57
	s_and_b64 s[50:51], s[36:37], exec
	s_cselect_b32 s50, s57, s58
	s_cmp_lt_u32 s28, 7
	s_movk_i32 s0, 0x10ff
	s_cselect_b32 s57, s64, s50
	s_cselect_b32 s58, 0xff, s0
	s_cselect_b32 s59, 0, 0x100
	s_add_i32 s66, s57, -1
	s_cmp_eq_u32 s56, 7
	s_cbranch_scc1 .Lrw_nd_pfslow
	s_cmp_eq_u32 s56, 8
	s_cbranch_scc1 .Lrw_nd_pfslow
	s_cmpk_eq_u32 s56, 0x87
	s_cbranch_scc1 .Lrw_nd_pfslow
	s_branch .Lrw_nd_nopf

.LBB0_1486:
	s_add_i32 s56, s28, 1
	v_readlane_b32 s0, v254, 14
	s_cmp_ge_u32 s56, s0
	s_cbranch_scc1 .Lrw_nd_nodma
	s_cmp_eq_u32 s56, 7
	s_cbranch_scc1 .Lrw_nd_nodma
	s_cmp_eq_u32 s56, 8
	s_cbranch_scc1 .Lrw_nd_nodma
	s_cmpk_eq_u32 s56, 0x87
	s_cbranch_scc1 .Lrw_nd_nodma
	s_lshl_b32 s57, s56, 5
	s_sub_i32 s64, 0xe0, s57
	s_and_b64 s[50:51], s[36:37], exec
	s_cselect_b32 s64, s57, s64
	s_sub_i32 s66, 0x11e0, s57
	s_and_b64 s[50:51], s[36:37], exec
	s_cselect_b32 s66, s57, s66
	s_cmp_lt_u32 s56, 8
	s_cselect_b32 s57, s64, s66
	s_add_i32 s66, s57, -1
	v_readfirstlane_b32 s64, v101
	s_mov_b64 s[50:51], exec
	s_and_b64 exec, exec, s[42:43]
	v_add_u32_e32 v28, s66, v93
	v_lshlrev_b32_e32 v28, 11, v28
	v_mov_b32_e32 v29, v164
	s_mov_b32 m0, s64
	v_lshl_add_u64 v[28:29], v[84:85], 0, v[28:29]
	global_load_lds_dwordx4 v[28:29], off
	v_add_u32_e32 v28, s66, v94
	v_lshlrev_b32_e32 v28, 11, v28
	v_mov_b32_e32 v29, v164
	s_add_i32 m0, s64, 0xf00
	v_lshl_add_u64 v[28:29], v[84:85], 0, v[28:29]
	global_load_lds_dwordx4 v[28:29], off
	v_add_u32_e32 v28, s66, v95
	v_lshlrev_b32_e32 v28, 11, v28
	v_mov_b32_e32 v29, v164
	s_add_i32 m0, s64, 0x1e00
	v_lshl_add_u64 v[28:29], v[84:85], 0, v[28:29]
	global_load_lds_dwordx4 v[28:29], off
	v_add_u32_e32 v28, s57, v93
	v_mov_b32_e32 v29, v164
	v_lshlrev_b64 v[28:29], 10, v[28:29]
	s_add_i32 m0, s64, 0x3300
	v_lshl_add_u64 v[28:29], v[86:87], 0, v[28:29]
	global_load_lds_dwordx4 v[28:29], off
	v_add_u32_e32 v28, s57, v94
	v_mov_b32_e32 v29, v164
	v_lshlrev_b64 v[28:29], 10, v[28:29]
	s_add_i32 m0, s64, 0x4200
	v_lshl_add_u64 v[28:29], v[86:87], 0, v[28:29]
	global_load_lds_dwordx4 v[28:29], off
	v_add_u32_e32 v28, s57, v95
	v_mov_b32_e32 v29, v164
	v_lshlrev_b64 v[28:29], 10, v[28:29]
	s_add_i32 m0, s64, 0x5100
	v_lshl_add_u64 v[28:29], v[86:87], 0, v[28:29]
	global_load_lds_dwordx4 v[28:29], off
	s_and_b64 exec, exec, s[44:45]
	v_add_u32_e32 v28, s66, v96
	v_lshlrev_b32_e32 v28, 11, v28
	v_mov_b32_e32 v29, v164
	s_add_i32 m0, s64, 0x2d00
	v_lshl_add_u64 v[28:29], v[84:85], 0, v[28:29]
	global_load_lds_dwordx4 v[28:29], off
	s_mov_b64 exec, s[50:51]
	s_and_b64 exec, exec, s[42:43]
	s_and_b64 exec, exec, s[48:49]
	v_add_u32_e32 v28, s57, v96
	v_mov_b32_e32 v29, v164
	v_lshlrev_b64 v[28:29], 10, v[28:29]
	s_add_i32 m0, s64, 0x6000
	v_lshl_add_u64 v[28:29], v[86:87], 0, v[28:29]
	global_load_lds_dwordx4 v[28:29], off
	s_mov_b64 exec, s[50:51]

.LBB0_1491:
	s_and_b64 s[54:55], s[42:43], s[54:55]
	s_and_saveexec_b64 s[50:51], s[54:55]
	s_cbranch_execz .LBB0_1496
	s_waitcnt vmcnt(2)
	s_cmp_eq_u32 s56, 7
	s_cbranch_scc1 .Lrw_nd_dostash
	s_cmp_eq_u32 s56, 8
	s_cbranch_scc1 .Lrw_nd_dostash
	s_cmpk_lg_u32 s56, 0x87
	s_cbranch_scc1 .LBB0_1496
.Lrw_nd_dostash:
	ds_write_b128 v101, v[32:35]
	ds_write_b128 v102, v[28:31]
	ds_write_b128 v103, v[36:39]
	s_and_saveexec_b64 s[54:55], s[44:45]
	ds_write_b128 v116, v[40:43]
	s_or_b64 exec, exec, s[54:55]
	ds_write_b128 v101, v[44:47] offset:13056
	ds_write_b128 v102, v[48:51] offset:13056
	ds_write_b128 v103, v[52:55] offset:13056
	s_and_b64 exec, exec, s[48:49]
	ds_write_b128 v116, v[56:59] offset:13056
